# in-proj (layer 1) and cross-q projection epilogues: the 8 row-scale loads of a unit issued together; no vmcnt(0) between row groups
# baseline (speedup 1.0000x reference)
.LBB0_571:
	v_lshl_add_u32 v138, s20, 8, v142
	v_ashrrev_i32_e32 v139, 31, v138
	v_lshl_add_u64 v[140:141], v[138:139], 2, s[6:7]
	flat_load_dword v139, v[140:141]
	global_load_dword v179, v[140:141], off offset:64
	global_load_dword v180, v[140:141], off offset:128
	global_load_dword v181, v[140:141], off offset:192
	global_load_dword v182, v[140:141], off offset:512
	global_load_dword v183, v[140:141], off offset:576
	global_load_dword v184, v[140:141], off offset:640
	global_load_dword v185, v[140:141], off offset:704
	s_mov_b32 s55, 0x800000
	v_lshl_or_b32 v146, s21, 8, v144
	s_mov_b64 s[52:53], 0x100
	s_waitcnt vmcnt(0) lgkmcnt(0)
	v_fmamk_f32 v139, v139, 0x3a800000, v221
	v_cmp_gt_f32_e32 vcc, s55, v139
	v_mul_f32_e32 v147, 0x4b800000, v139
	s_nop 0
	v_cndmask_b32_e32 v139, v139, v147, vcc
	v_rsq_f32_e32 v139, v139
	s_nop 0
	v_mul_f32_e32 v147, 0x45800000, v139
	v_cndmask_b32_e32 v148, v139, v147, vcc
	v_pk_mul_f32 v[126:127], v[126:127], v[148:149] op_sel_hi:[1,0]
	v_pk_mul_f32 v[124:125], v[124:125], v[148:149] op_sel_hi:[1,0]
	v_pk_mul_f32 v[120:121], v[120:121], v[148:149] op_sel_hi:[1,0]
	v_pk_mul_f32 v[122:123], v[122:123], v[148:149] op_sel_hi:[1,0]
	v_cvt_pk_bf16_f32 v124, v124, v125
	v_cvt_pk_bf16_f32 v125, v126, v127
	v_cvt_pk_bf16_f32 v126, v120, v121
	v_mov_b64_e32 v[120:121], s[8:9]
	v_ashrrev_i32_e32 v147, 31, v146
	v_cvt_pk_bf16_f32 v127, v122, v123
	v_mad_i64_i32 v[150:151], s[20:21], v138, s97, v[120:121]
	v_lshlrev_b64 v[122:123], 1, v[146:147]
	v_lshl_add_u64 v[146:147], v[150:151], 0, v[122:123]
	global_store_dwordx4 v[146:147], v[124:127], off
	v_pk_mul_f32 v[118:119], v[118:119], v[148:149] op_sel_hi:[1,0]
	v_pk_mul_f32 v[116:117], v[116:117], v[148:149] op_sel_hi:[1,0]
	v_pk_mul_f32 v[124:125], v[114:115], v[148:149] op_sel_hi:[1,0]
	v_pk_mul_f32 v[114:115], v[112:113], v[148:149] op_sel_hi:[1,0]
	v_cvt_pk_bf16_f32 v112, v116, v117
	v_cvt_pk_bf16_f32 v113, v118, v119
	v_cvt_pk_bf16_f32 v114, v114, v115
	v_cvt_pk_bf16_f32 v115, v124, v125
	global_store_dwordx4 v[146:147], v[112:115], off offset:256
	s_nop 1
	v_or_b32_e32 v112, 16, v138
	v_ashrrev_i32_e32 v113, 31, v112
	v_lshl_add_u64 v[114:115], v[112:113], 2, s[6:7]
	s_nop 1
	v_mov_b32_e32 v113, v179
	v_fmamk_f32 v113, v113, 0x3a800000, v221
	v_cmp_gt_f32_e32 vcc, s55, v113
	v_mul_f32_e32 v114, 0x4b800000, v113
	s_nop 0
	v_cndmask_b32_e32 v113, v113, v114, vcc
	v_rsq_f32_e32 v113, v113
	s_nop 0
	v_mul_f32_e32 v114, 0x45800000, v113
	v_cndmask_b32_e32 v114, v113, v114, vcc
	v_pk_mul_f32 v[108:109], v[108:109], v[114:115] op_sel_hi:[1,0]
	v_pk_mul_f32 v[110:111], v[110:111], v[114:115] op_sel_hi:[1,0]
	v_pk_mul_f32 v[116:117], v[106:107], v[114:115] op_sel_hi:[1,0]
	v_pk_mul_f32 v[106:107], v[104:105], v[114:115] op_sel_hi:[1,0]
	v_cvt_pk_bf16_f32 v104, v108, v109
	v_mad_i64_i32 v[108:109], s[20:21], v112, s97, v[120:121]
	v_cvt_pk_bf16_f32 v105, v110, v111
	v_cvt_pk_bf16_f32 v106, v106, v107
	v_cvt_pk_bf16_f32 v107, v116, v117
	v_lshl_add_u64 v[108:109], v[108:109], 0, v[122:123]
	global_store_dwordx4 v[108:109], v[104:107], off
	v_pk_mul_f32 v[102:103], v[102:103], v[114:115] op_sel_hi:[1,0]
	v_pk_mul_f32 v[100:101], v[100:101], v[114:115] op_sel_hi:[1,0]
	v_pk_mul_f32 v[104:105], v[98:99], v[114:115] op_sel_hi:[1,0]
	v_pk_mul_f32 v[98:99], v[96:97], v[114:115] op_sel_hi:[1,0]
	v_cvt_pk_bf16_f32 v96, v100, v101
	v_cvt_pk_bf16_f32 v97, v102, v103
	v_cvt_pk_bf16_f32 v98, v98, v99
	v_cvt_pk_bf16_f32 v99, v104, v105
	global_store_dwordx4 v[108:109], v[96:99], off offset:256
	s_nop 1
	v_or_b32_e32 v96, 32, v138
	v_ashrrev_i32_e32 v97, 31, v96
	v_lshl_add_u64 v[98:99], v[96:97], 2, s[6:7]
	s_nop 1
	v_mov_b32_e32 v97, v180
	v_fmamk_f32 v97, v97, 0x3a800000, v221
	v_cmp_gt_f32_e32 vcc, s55, v97
	v_mul_f32_e32 v98, 0x4b800000, v97
	s_nop 0
	v_cndmask_b32_e32 v97, v97, v98, vcc
	v_rsq_f32_e32 v97, v97
	s_nop 0
	v_mul_f32_e32 v98, 0x45800000, v97
	v_cndmask_b32_e32 v98, v97, v98, vcc
	v_pk_mul_f32 v[92:93], v[92:93], v[98:99] op_sel_hi:[1,0]
	v_pk_mul_f32 v[94:95], v[94:95], v[98:99] op_sel_hi:[1,0]
	v_pk_mul_f32 v[100:101], v[90:91], v[98:99] op_sel_hi:[1,0]
	v_pk_mul_f32 v[90:91], v[88:89], v[98:99] op_sel_hi:[1,0]
	v_cvt_pk_bf16_f32 v88, v92, v93
	v_mad_i64_i32 v[92:93], s[20:21], v96, s97, v[120:121]
	v_cvt_pk_bf16_f32 v89, v94, v95
	v_cvt_pk_bf16_f32 v90, v90, v91
	v_cvt_pk_bf16_f32 v91, v100, v101
	v_lshl_add_u64 v[92:93], v[92:93], 0, v[122:123]
	global_store_dwordx4 v[92:93], v[88:91], off
	v_pk_mul_f32 v[86:87], v[86:87], v[98:99] op_sel_hi:[1,0]
	v_pk_mul_f32 v[84:85], v[84:85], v[98:99] op_sel_hi:[1,0]
	v_pk_mul_f32 v[88:89], v[82:83], v[98:99] op_sel_hi:[1,0]
	v_pk_mul_f32 v[82:83], v[80:81], v[98:99] op_sel_hi:[1,0]
	v_cvt_pk_bf16_f32 v80, v84, v85
	v_cvt_pk_bf16_f32 v81, v86, v87
	v_cvt_pk_bf16_f32 v82, v82, v83
	v_cvt_pk_bf16_f32 v83, v88, v89
	global_store_dwordx4 v[92:93], v[80:83], off offset:256
	s_nop 1
	v_or_b32_e32 v80, 48, v138
	v_ashrrev_i32_e32 v81, 31, v80
	v_lshl_add_u64 v[82:83], v[80:81], 2, s[6:7]
	s_nop 1
	v_mov_b32_e32 v81, v181
	v_fmamk_f32 v81, v81, 0x3a800000, v221
	v_cmp_gt_f32_e32 vcc, s55, v81
	v_mul_f32_e32 v82, 0x4b800000, v81
	s_nop 0
	v_cndmask_b32_e32 v81, v81, v82, vcc
	v_rsq_f32_e32 v81, v81
	s_nop 0
	v_mul_f32_e32 v82, 0x45800000, v81
	v_cndmask_b32_e32 v82, v81, v82, vcc
	v_pk_mul_f32 v[76:77], v[76:77], v[82:83] op_sel_hi:[1,0]
	v_pk_mul_f32 v[78:79], v[78:79], v[82:83] op_sel_hi:[1,0]
	v_pk_mul_f32 v[84:85], v[74:75], v[82:83] op_sel_hi:[1,0]
	v_pk_mul_f32 v[74:75], v[72:73], v[82:83] op_sel_hi:[1,0]
	v_cvt_pk_bf16_f32 v72, v76, v77
	v_mad_i64_i32 v[76:77], s[20:21], v80, s97, v[120:121]
	v_cvt_pk_bf16_f32 v73, v78, v79
	v_cvt_pk_bf16_f32 v74, v74, v75
	v_cvt_pk_bf16_f32 v75, v84, v85
	v_lshl_add_u64 v[76:77], v[76:77], 0, v[122:123]
	global_store_dwordx4 v[76:77], v[72:75], off
	v_pk_mul_f32 v[70:71], v[70:71], v[82:83] op_sel_hi:[1,0]
	v_pk_mul_f32 v[68:69], v[68:69], v[82:83] op_sel_hi:[1,0]
	v_pk_mul_f32 v[72:73], v[66:67], v[82:83] op_sel_hi:[1,0]
	v_pk_mul_f32 v[66:67], v[64:65], v[82:83] op_sel_hi:[1,0]
	v_cvt_pk_bf16_f32 v64, v68, v69
	v_cvt_pk_bf16_f32 v65, v70, v71
	v_cvt_pk_bf16_f32 v66, v66, v67
	v_cvt_pk_bf16_f32 v67, v72, v73
	global_store_dwordx4 v[76:77], v[64:67], off offset:256
	s_nop 1
	v_mov_b32_e32 v64, v182
	s_nop 0
	v_add_u32_e32 v65, 0x80, v138
	v_fmamk_f32 v64, v64, 0x3a800000, v221
	v_cmp_gt_f32_e32 vcc, s55, v64
	v_mul_f32_e32 v66, 0x4b800000, v64
	s_nop 0
	v_cndmask_b32_e32 v64, v64, v66, vcc
	v_rsq_f32_e32 v64, v64
	s_nop 0
	v_mul_f32_e32 v66, 0x45800000, v64
	v_cndmask_b32_e32 v64, v64, v66, vcc
	v_pk_mul_f32 v[60:61], v[60:61], v[64:65] op_sel_hi:[1,0]
	v_pk_mul_f32 v[62:63], v[62:63], v[64:65] op_sel_hi:[1,0]
	v_pk_mul_f32 v[66:67], v[58:59], v[64:65] op_sel_hi:[1,0]
	v_pk_mul_f32 v[58:59], v[56:57], v[64:65] op_sel_hi:[1,0]
	v_cvt_pk_bf16_f32 v56, v60, v61
	v_mad_i64_i32 v[60:61], s[20:21], v65, s97, v[120:121]
	v_cvt_pk_bf16_f32 v57, v62, v63
	v_cvt_pk_bf16_f32 v58, v58, v59
	v_cvt_pk_bf16_f32 v59, v66, v67
	v_lshl_add_u64 v[60:61], v[60:61], 0, v[122:123]
	global_store_dwordx4 v[60:61], v[56:59], off
	v_pk_mul_f32 v[54:55], v[54:55], v[64:65] op_sel_hi:[1,0]
	v_pk_mul_f32 v[52:53], v[52:53], v[64:65] op_sel_hi:[1,0]
	v_pk_mul_f32 v[56:57], v[50:51], v[64:65] op_sel_hi:[1,0]
	v_pk_mul_f32 v[50:51], v[48:49], v[64:65] op_sel_hi:[1,0]
	v_cvt_pk_bf16_f32 v48, v52, v53
	v_cvt_pk_bf16_f32 v49, v54, v55
	v_cvt_pk_bf16_f32 v50, v50, v51
	v_cvt_pk_bf16_f32 v51, v56, v57
	global_store_dwordx4 v[60:61], v[48:51], off offset:256
	s_nop 1
	v_mov_b32_e32 v48, v183
	s_nop 0
	v_add_u32_e32 v49, 0x90, v138
	v_fmamk_f32 v48, v48, 0x3a800000, v221
	v_cmp_gt_f32_e32 vcc, s55, v48
	v_mul_f32_e32 v50, 0x4b800000, v48
	s_nop 0
	v_cndmask_b32_e32 v48, v48, v50, vcc
	v_rsq_f32_e32 v48, v48
	s_nop 0
	v_mul_f32_e32 v50, 0x45800000, v48
	v_cndmask_b32_e32 v48, v48, v50, vcc
	v_pk_mul_f32 v[44:45], v[44:45], v[48:49] op_sel_hi:[1,0]
	v_pk_mul_f32 v[46:47], v[46:47], v[48:49] op_sel_hi:[1,0]
	v_pk_mul_f32 v[50:51], v[42:43], v[48:49] op_sel_hi:[1,0]
	v_pk_mul_f32 v[42:43], v[40:41], v[48:49] op_sel_hi:[1,0]
	v_cvt_pk_bf16_f32 v40, v44, v45
	v_mad_i64_i32 v[44:45], s[20:21], v49, s97, v[120:121]
	v_cvt_pk_bf16_f32 v41, v46, v47
	v_cvt_pk_bf16_f32 v42, v42, v43
	v_cvt_pk_bf16_f32 v43, v50, v51
	v_lshl_add_u64 v[44:45], v[44:45], 0, v[122:123]
	global_store_dwordx4 v[44:45], v[40:43], off
	v_pk_mul_f32 v[38:39], v[38:39], v[48:49] op_sel_hi:[1,0]
	v_pk_mul_f32 v[36:37], v[36:37], v[48:49] op_sel_hi:[1,0]
	v_pk_mul_f32 v[40:41], v[34:35], v[48:49] op_sel_hi:[1,0]
	v_pk_mul_f32 v[34:35], v[32:33], v[48:49] op_sel_hi:[1,0]
	v_cvt_pk_bf16_f32 v32, v36, v37
	v_cvt_pk_bf16_f32 v33, v38, v39
	v_cvt_pk_bf16_f32 v34, v34, v35
	v_cvt_pk_bf16_f32 v35, v40, v41
	global_store_dwordx4 v[44:45], v[32:35], off offset:256
	s_nop 1
	v_mov_b32_e32 v32, v184
	s_nop 0
	v_add_u32_e32 v33, 0xa0, v138
	v_fmamk_f32 v32, v32, 0x3a800000, v221
	v_cmp_gt_f32_e32 vcc, s55, v32
	v_mul_f32_e32 v34, 0x4b800000, v32
	s_nop 0
	v_cndmask_b32_e32 v32, v32, v34, vcc
	v_rsq_f32_e32 v32, v32
	s_nop 0
	v_mul_f32_e32 v34, 0x45800000, v32
	v_cndmask_b32_e32 v32, v32, v34, vcc
	v_pk_mul_f32 v[28:29], v[28:29], v[32:33] op_sel_hi:[1,0]
	v_pk_mul_f32 v[30:31], v[30:31], v[32:33] op_sel_hi:[1,0]
	v_pk_mul_f32 v[34:35], v[26:27], v[32:33] op_sel_hi:[1,0]
	v_pk_mul_f32 v[26:27], v[24:25], v[32:33] op_sel_hi:[1,0]
	v_cvt_pk_bf16_f32 v24, v28, v29
	v_mad_i64_i32 v[28:29], s[20:21], v33, s97, v[120:121]
	v_cvt_pk_bf16_f32 v25, v30, v31
	v_cvt_pk_bf16_f32 v26, v26, v27
	v_cvt_pk_bf16_f32 v27, v34, v35
	v_lshl_add_u64 v[28:29], v[28:29], 0, v[122:123]
	global_store_dwordx4 v[28:29], v[24:27], off
	v_pk_mul_f32 v[22:23], v[22:23], v[32:33] op_sel_hi:[1,0]
	v_pk_mul_f32 v[20:21], v[20:21], v[32:33] op_sel_hi:[1,0]
	v_pk_mul_f32 v[24:25], v[18:19], v[32:33] op_sel_hi:[1,0]
	v_pk_mul_f32 v[18:19], v[16:17], v[32:33] op_sel_hi:[1,0]
	v_cvt_pk_bf16_f32 v16, v20, v21
	v_cvt_pk_bf16_f32 v17, v22, v23
	v_cvt_pk_bf16_f32 v18, v18, v19
	v_cvt_pk_bf16_f32 v19, v24, v25
	global_store_dwordx4 v[28:29], v[16:19], off offset:256
	s_nop 1
	v_mov_b32_e32 v16, v185
	s_nop 0
	v_add_u32_e32 v17, 0xb0, v138
	v_fmamk_f32 v16, v16, 0x3a800000, v221
	v_cmp_gt_f32_e32 vcc, s55, v16
	v_mul_f32_e32 v18, 0x4b800000, v16
	s_nop 0
	v_cndmask_b32_e32 v16, v16, v18, vcc
	v_rsq_f32_e32 v16, v16
	s_nop 0
	v_mul_f32_e32 v18, 0x45800000, v16
	v_cndmask_b32_e32 v16, v16, v18, vcc
	v_pk_mul_f32 v[12:13], v[12:13], v[16:17] op_sel_hi:[1,0]
	v_pk_mul_f32 v[14:15], v[14:15], v[16:17] op_sel_hi:[1,0]
	v_pk_mul_f32 v[18:19], v[10:11], v[16:17] op_sel_hi:[1,0]
	v_pk_mul_f32 v[10:11], v[8:9], v[16:17] op_sel_hi:[1,0]
	v_cvt_pk_bf16_f32 v8, v12, v13
	v_mad_i64_i32 v[12:13], s[20:21], v17, s97, v[120:121]
	v_cvt_pk_bf16_f32 v9, v14, v15
	v_cvt_pk_bf16_f32 v10, v10, v11
	v_cvt_pk_bf16_f32 v11, v18, v19
	v_lshl_add_u64 v[12:13], v[12:13], 0, v[122:123]
	global_store_dwordx4 v[12:13], v[8:11], off
	v_pk_mul_f32 v[6:7], v[6:7], v[16:17] op_sel_hi:[1,0]
	v_pk_mul_f32 v[4:5], v[4:5], v[16:17] op_sel_hi:[1,0]
	v_pk_mul_f32 v[8:9], v[2:3], v[16:17] op_sel_hi:[1,0]
	v_pk_mul_f32 v[2:3], v[0:1], v[16:17] op_sel_hi:[1,0]
	v_cvt_pk_bf16_f32 v0, v4, v5
	v_cvt_pk_bf16_f32 v1, v6, v7
	v_cvt_pk_bf16_f32 v2, v2, v3
	v_cvt_pk_bf16_f32 v3, v8, v9
	s_mov_b64 s[20:21], -1
	s_andn2_b64 vcc, exec, s[2:3]
	global_store_dwordx4 v[12:13], v[0:3], off offset:256
	s_cbranch_vccnz .LBB0_564
	s_andn2_b64 vcc, exec, s[4:5]
	s_cbranch_vccnz .LBB0_563
	s_barrier
	s_branch .LBB0_563

.LBB0_1475:
	v_lshl_add_u32 v140, s20, 8, v142
	v_ashrrev_i32_e32 v141, 31, v140
	v_lshl_add_u64 v[138:139], v[140:141], 2, s[8:9]
	flat_load_dword v147, v[138:139]
	global_load_dword v179, v[138:139], off offset:64
	global_load_dword v180, v[138:139], off offset:128
	global_load_dword v181, v[138:139], off offset:192
	global_load_dword v182, v[138:139], off offset:512
	global_load_dword v183, v[138:139], off offset:576
	global_load_dword v184, v[138:139], off offset:640
	global_load_dword v185, v[138:139], off offset:704
	s_mov_b32 s0, 0x800000
	v_lshl_or_b32 v146, s21, 8, v144
	s_mov_b64 s[20:21], 0x24000
	s_mov_b32 s13, 0x28000
	s_waitcnt vmcnt(0) lgkmcnt(0)
	v_fmamk_f32 v147, v147, 0x3a800000, v221
	v_cmp_gt_f32_e32 vcc, s0, v147
	v_mul_f32_e32 v148, 0x4b800000, v147
	s_nop 0
	v_cndmask_b32_e32 v147, v147, v148, vcc
	v_rsq_f32_e32 v147, v147
	s_nop 0
	v_mul_f32_e32 v148, 0x45800000, v147
	v_cndmask_b32_e32 v148, v147, v148, vcc
	v_pk_mul_f32 v[126:127], v[126:127], v[148:149] op_sel_hi:[1,0]
	v_pk_mul_f32 v[124:125], v[124:125], v[148:149] op_sel_hi:[1,0]
	v_pk_mul_f32 v[120:121], v[120:121], v[148:149] op_sel_hi:[1,0]
	v_pk_mul_f32 v[122:123], v[122:123], v[148:149] op_sel_hi:[1,0]
	v_cvt_pk_bf16_f32 v124, v124, v125
	v_cvt_pk_bf16_f32 v125, v126, v127
	v_cvt_pk_bf16_f32 v126, v120, v121
	v_lshlrev_b64 v[120:121], 10, v[140:141]
	v_ashrrev_i32_e32 v147, 31, v146
	v_cvt_pk_bf16_f32 v127, v122, v123
	v_lshl_add_u64 v[120:121], s[6:7], 0, v[120:121]
	v_lshlrev_b64 v[122:123], 1, v[146:147]
	v_lshl_add_u64 v[120:121], v[120:121], 0, v[122:123]
	global_store_dwordx4 v[120:121], v[124:127], off
	v_pk_mul_f32 v[118:119], v[118:119], v[148:149] op_sel_hi:[1,0]
	v_pk_mul_f32 v[116:117], v[116:117], v[148:149] op_sel_hi:[1,0]
	v_pk_mul_f32 v[124:125], v[114:115], v[148:149] op_sel_hi:[1,0]
	v_pk_mul_f32 v[114:115], v[112:113], v[148:149] op_sel_hi:[1,0]
	v_cvt_pk_bf16_f32 v112, v116, v117
	v_cvt_pk_bf16_f32 v113, v118, v119
	v_cvt_pk_bf16_f32 v114, v114, v115
	v_cvt_pk_bf16_f32 v115, v124, v125
	global_store_dwordx4 v[120:121], v[112:115], off offset:256
	s_nop 1
	v_mov_b32_e32 v114, v179
	s_nop 0
	v_or_b32_e32 v112, 16, v140
	v_ashrrev_i32_e32 v113, 31, v112
	v_fmamk_f32 v114, v114, 0x3a800000, v221
	v_cmp_gt_f32_e32 vcc, s0, v114
	v_mul_f32_e32 v115, 0x4b800000, v114
	s_nop 0
	v_cndmask_b32_e32 v114, v114, v115, vcc
	v_rsq_f32_e32 v114, v114
	s_nop 0
	v_mul_f32_e32 v115, 0x45800000, v114
	v_cndmask_b32_e32 v114, v114, v115, vcc
	v_pk_mul_f32 v[108:109], v[108:109], v[114:115] op_sel_hi:[1,0]
	v_pk_mul_f32 v[116:117], v[106:107], v[114:115] op_sel_hi:[1,0]
	v_pk_mul_f32 v[106:107], v[104:105], v[114:115] op_sel_hi:[1,0]
	v_cvt_pk_bf16_f32 v104, v108, v109
	v_lshlrev_b64 v[108:109], 10, v[112:113]
	v_pk_mul_f32 v[110:111], v[110:111], v[114:115] op_sel_hi:[1,0]
	v_lshl_add_u64 v[108:109], s[6:7], 0, v[108:109]
	v_cvt_pk_bf16_f32 v105, v110, v111
	v_cvt_pk_bf16_f32 v106, v106, v107
	v_cvt_pk_bf16_f32 v107, v116, v117
	v_lshl_add_u64 v[108:109], v[108:109], 0, v[122:123]
	global_store_dwordx4 v[108:109], v[104:107], off
	v_pk_mul_f32 v[102:103], v[102:103], v[114:115] op_sel_hi:[1,0]
	v_pk_mul_f32 v[100:101], v[100:101], v[114:115] op_sel_hi:[1,0]
	v_pk_mul_f32 v[104:105], v[98:99], v[114:115] op_sel_hi:[1,0]
	v_pk_mul_f32 v[98:99], v[96:97], v[114:115] op_sel_hi:[1,0]
	v_cvt_pk_bf16_f32 v96, v100, v101
	v_cvt_pk_bf16_f32 v97, v102, v103
	v_cvt_pk_bf16_f32 v98, v98, v99
	v_cvt_pk_bf16_f32 v99, v104, v105
	global_store_dwordx4 v[108:109], v[96:99], off offset:256
	s_nop 1
	v_mov_b32_e32 v98, v180
	s_nop 0
	v_or_b32_e32 v96, 32, v140
	v_ashrrev_i32_e32 v97, 31, v96
	v_fmamk_f32 v98, v98, 0x3a800000, v221
	v_cmp_gt_f32_e32 vcc, s0, v98
	v_mul_f32_e32 v99, 0x4b800000, v98
	s_nop 0
	v_cndmask_b32_e32 v98, v98, v99, vcc
	v_rsq_f32_e32 v98, v98
	s_nop 0
	v_mul_f32_e32 v99, 0x45800000, v98
	v_cndmask_b32_e32 v98, v98, v99, vcc
	v_pk_mul_f32 v[92:93], v[92:93], v[98:99] op_sel_hi:[1,0]
	v_pk_mul_f32 v[100:101], v[90:91], v[98:99] op_sel_hi:[1,0]
	v_pk_mul_f32 v[90:91], v[88:89], v[98:99] op_sel_hi:[1,0]
	v_cvt_pk_bf16_f32 v88, v92, v93
	v_lshlrev_b64 v[92:93], 10, v[96:97]
	v_pk_mul_f32 v[94:95], v[94:95], v[98:99] op_sel_hi:[1,0]
	v_lshl_add_u64 v[92:93], s[6:7], 0, v[92:93]
	v_cvt_pk_bf16_f32 v89, v94, v95
	v_cvt_pk_bf16_f32 v90, v90, v91
	v_cvt_pk_bf16_f32 v91, v100, v101
	v_lshl_add_u64 v[92:93], v[92:93], 0, v[122:123]
	global_store_dwordx4 v[92:93], v[88:91], off
	v_pk_mul_f32 v[86:87], v[86:87], v[98:99] op_sel_hi:[1,0]
	v_pk_mul_f32 v[84:85], v[84:85], v[98:99] op_sel_hi:[1,0]
	v_pk_mul_f32 v[88:89], v[82:83], v[98:99] op_sel_hi:[1,0]
	v_pk_mul_f32 v[82:83], v[80:81], v[98:99] op_sel_hi:[1,0]
	v_cvt_pk_bf16_f32 v80, v84, v85
	v_cvt_pk_bf16_f32 v81, v86, v87
	v_cvt_pk_bf16_f32 v82, v82, v83
	v_cvt_pk_bf16_f32 v83, v88, v89
	global_store_dwordx4 v[92:93], v[80:83], off offset:256
	s_nop 1
	v_mov_b32_e32 v82, v181
	s_nop 0
	v_or_b32_e32 v80, 48, v140
	v_ashrrev_i32_e32 v81, 31, v80
	v_fmamk_f32 v82, v82, 0x3a800000, v221
	v_cmp_gt_f32_e32 vcc, s0, v82
	v_mul_f32_e32 v83, 0x4b800000, v82
	s_nop 0
	v_cndmask_b32_e32 v82, v82, v83, vcc
	v_rsq_f32_e32 v82, v82
	s_nop 0
	v_mul_f32_e32 v83, 0x45800000, v82
	v_cndmask_b32_e32 v82, v82, v83, vcc
	v_pk_mul_f32 v[76:77], v[76:77], v[82:83] op_sel_hi:[1,0]
	v_pk_mul_f32 v[84:85], v[74:75], v[82:83] op_sel_hi:[1,0]
	v_pk_mul_f32 v[74:75], v[72:73], v[82:83] op_sel_hi:[1,0]
	v_cvt_pk_bf16_f32 v72, v76, v77
	v_lshlrev_b64 v[76:77], 10, v[80:81]
	v_pk_mul_f32 v[78:79], v[78:79], v[82:83] op_sel_hi:[1,0]
	v_lshl_add_u64 v[76:77], s[6:7], 0, v[76:77]
	v_cvt_pk_bf16_f32 v73, v78, v79
	v_cvt_pk_bf16_f32 v74, v74, v75
	v_cvt_pk_bf16_f32 v75, v84, v85
	v_lshl_add_u64 v[76:77], v[76:77], 0, v[122:123]
	global_store_dwordx4 v[76:77], v[72:75], off
	v_pk_mul_f32 v[70:71], v[70:71], v[82:83] op_sel_hi:[1,0]
	v_pk_mul_f32 v[68:69], v[68:69], v[82:83] op_sel_hi:[1,0]
	v_pk_mul_f32 v[72:73], v[66:67], v[82:83] op_sel_hi:[1,0]
	v_pk_mul_f32 v[66:67], v[64:65], v[82:83] op_sel_hi:[1,0]
	v_cvt_pk_bf16_f32 v64, v68, v69
	v_cvt_pk_bf16_f32 v65, v70, v71
	v_cvt_pk_bf16_f32 v66, v66, v67
	v_cvt_pk_bf16_f32 v67, v72, v73
	global_store_dwordx4 v[76:77], v[64:67], off offset:256
	s_nop 1
	v_mov_b32_e32 v64, v182
	v_fmamk_f32 v64, v64, 0x3a800000, v221
	v_cmp_gt_f32_e32 vcc, s0, v64
	v_mul_f32_e32 v65, 0x4b800000, v64
	s_nop 0
	v_cndmask_b32_e32 v64, v64, v65, vcc
	v_rsq_f32_e32 v64, v64
	s_nop 0
	v_mul_f32_e32 v65, 0x45800000, v64
	v_cndmask_b32_e32 v64, v64, v65, vcc
	v_pk_mul_f32 v[62:63], v[62:63], v[64:65] op_sel_hi:[1,0]
	v_pk_mul_f32 v[60:61], v[60:61], v[64:65] op_sel_hi:[1,0]
	v_pk_mul_f32 v[66:67], v[58:59], v[64:65] op_sel_hi:[1,0]
	v_pk_mul_f32 v[58:59], v[56:57], v[64:65] op_sel_hi:[1,0]
	v_cvt_pk_bf16_f32 v57, v62, v63
	v_add_co_u32_e32 v62, vcc, s55, v120
	v_cvt_pk_bf16_f32 v56, v60, v61
	v_cvt_pk_bf16_f32 v58, v58, v59
	v_cvt_pk_bf16_f32 v59, v66, v67
	v_addc_co_u32_e32 v63, vcc, 0, v121, vcc
	global_store_dwordx4 v[62:63], v[56:59], off
	v_pk_mul_f32 v[54:55], v[54:55], v[64:65] op_sel_hi:[1,0]
	v_pk_mul_f32 v[52:53], v[52:53], v[64:65] op_sel_hi:[1,0]
	v_pk_mul_f32 v[56:57], v[50:51], v[64:65] op_sel_hi:[1,0]
	v_pk_mul_f32 v[50:51], v[48:49], v[64:65] op_sel_hi:[1,0]
	v_lshl_add_u64 v[60:61], v[120:121], 0, s[78:79]
	v_cvt_pk_bf16_f32 v48, v52, v53
	v_cvt_pk_bf16_f32 v49, v54, v55
	v_cvt_pk_bf16_f32 v50, v50, v51
	v_cvt_pk_bf16_f32 v51, v56, v57
	global_store_dwordx4 v[60:61], v[48:51], off offset:256
	s_nop 1
	v_mov_b32_e32 v48, v183
	v_fmamk_f32 v48, v48, 0x3a800000, v221
	v_cmp_gt_f32_e32 vcc, s0, v48
	v_mul_f32_e32 v49, 0x4b800000, v48
	s_nop 0
	v_cndmask_b32_e32 v48, v48, v49, vcc
	v_rsq_f32_e32 v48, v48
	s_nop 0
	v_mul_f32_e32 v49, 0x45800000, v48
	v_cndmask_b32_e32 v48, v48, v49, vcc
	v_pk_mul_f32 v[46:47], v[46:47], v[48:49] op_sel_hi:[1,0]
	v_pk_mul_f32 v[44:45], v[44:45], v[48:49] op_sel_hi:[1,0]
	v_pk_mul_f32 v[50:51], v[42:43], v[48:49] op_sel_hi:[1,0]
	v_pk_mul_f32 v[42:43], v[40:41], v[48:49] op_sel_hi:[1,0]
	v_cvt_pk_bf16_f32 v41, v46, v47
	v_add_co_u32_e32 v46, vcc, s1, v120
	v_cvt_pk_bf16_f32 v40, v44, v45
	v_cvt_pk_bf16_f32 v42, v42, v43
	v_cvt_pk_bf16_f32 v43, v50, v51
	v_addc_co_u32_e32 v47, vcc, 0, v121, vcc
	global_store_dwordx4 v[46:47], v[40:43], off
	v_pk_mul_f32 v[38:39], v[38:39], v[48:49] op_sel_hi:[1,0]
	v_pk_mul_f32 v[36:37], v[36:37], v[48:49] op_sel_hi:[1,0]
	v_pk_mul_f32 v[40:41], v[34:35], v[48:49] op_sel_hi:[1,0]
	v_pk_mul_f32 v[34:35], v[32:33], v[48:49] op_sel_hi:[1,0]
	v_lshl_add_u64 v[44:45], v[120:121], 0, s[20:21]
	v_cvt_pk_bf16_f32 v32, v36, v37
	v_cvt_pk_bf16_f32 v33, v38, v39
	v_cvt_pk_bf16_f32 v34, v34, v35
	v_cvt_pk_bf16_f32 v35, v40, v41
	global_store_dwordx4 v[44:45], v[32:35], off offset:256
	s_nop 1
	v_mov_b32_e32 v32, v184
	s_mov_b64 s[20:21], 0x28000
	v_fmamk_f32 v32, v32, 0x3a800000, v221
	v_cmp_gt_f32_e32 vcc, s0, v32
	v_mul_f32_e32 v33, 0x4b800000, v32
	s_nop 0
	v_cndmask_b32_e32 v32, v32, v33, vcc
	v_rsq_f32_e32 v32, v32
	s_nop 0
	v_mul_f32_e32 v33, 0x45800000, v32
	v_cndmask_b32_e32 v32, v32, v33, vcc
	v_pk_mul_f32 v[30:31], v[30:31], v[32:33] op_sel_hi:[1,0]
	v_pk_mul_f32 v[28:29], v[28:29], v[32:33] op_sel_hi:[1,0]
	v_pk_mul_f32 v[34:35], v[26:27], v[32:33] op_sel_hi:[1,0]
	v_pk_mul_f32 v[26:27], v[24:25], v[32:33] op_sel_hi:[1,0]
	v_cvt_pk_bf16_f32 v25, v30, v31
	v_add_co_u32_e32 v30, vcc, s13, v120
	v_cvt_pk_bf16_f32 v24, v28, v29
	v_cvt_pk_bf16_f32 v26, v26, v27
	v_cvt_pk_bf16_f32 v27, v34, v35
	v_addc_co_u32_e32 v31, vcc, 0, v121, vcc
	global_store_dwordx4 v[30:31], v[24:27], off
	v_pk_mul_f32 v[22:23], v[22:23], v[32:33] op_sel_hi:[1,0]
	v_pk_mul_f32 v[20:21], v[20:21], v[32:33] op_sel_hi:[1,0]
	v_pk_mul_f32 v[24:25], v[18:19], v[32:33] op_sel_hi:[1,0]
	v_pk_mul_f32 v[18:19], v[16:17], v[32:33] op_sel_hi:[1,0]
	v_lshl_add_u64 v[28:29], v[120:121], 0, s[20:21]
	v_cvt_pk_bf16_f32 v16, v20, v21
	v_cvt_pk_bf16_f32 v17, v22, v23
	v_cvt_pk_bf16_f32 v18, v18, v19
	v_cvt_pk_bf16_f32 v19, v24, v25
	global_store_dwordx4 v[28:29], v[16:19], off offset:256
	s_nop 1
	v_mov_b32_e32 v16, v185
	s_mov_b32 s13, 0x2c000
	s_mov_b64 s[20:21], 0x2c000
	v_fmamk_f32 v16, v16, 0x3a800000, v221
	v_cmp_gt_f32_e32 vcc, s0, v16
	v_mul_f32_e32 v17, 0x4b800000, v16
	s_nop 0
	v_cndmask_b32_e32 v16, v16, v17, vcc
	v_rsq_f32_e32 v16, v16
	s_nop 0
	v_mul_f32_e32 v17, 0x45800000, v16
	v_cndmask_b32_e32 v16, v16, v17, vcc
	v_pk_mul_f32 v[14:15], v[14:15], v[16:17] op_sel_hi:[1,0]
	v_pk_mul_f32 v[12:13], v[12:13], v[16:17] op_sel_hi:[1,0]
	v_pk_mul_f32 v[18:19], v[10:11], v[16:17] op_sel_hi:[1,0]
	v_pk_mul_f32 v[10:11], v[8:9], v[16:17] op_sel_hi:[1,0]
	v_cvt_pk_bf16_f32 v9, v14, v15
	v_add_co_u32_e32 v14, vcc, s13, v120
	v_cvt_pk_bf16_f32 v8, v12, v13
	v_cvt_pk_bf16_f32 v10, v10, v11
	v_cvt_pk_bf16_f32 v11, v18, v19
	v_addc_co_u32_e32 v15, vcc, 0, v121, vcc
	global_store_dwordx4 v[14:15], v[8:11], off
	v_pk_mul_f32 v[6:7], v[6:7], v[16:17] op_sel_hi:[1,0]
	v_pk_mul_f32 v[4:5], v[4:5], v[16:17] op_sel_hi:[1,0]
	v_pk_mul_f32 v[8:9], v[2:3], v[16:17] op_sel_hi:[1,0]
	v_pk_mul_f32 v[2:3], v[0:1], v[16:17] op_sel_hi:[1,0]
	v_lshl_add_u64 v[12:13], v[120:121], 0, s[20:21]
	v_cvt_pk_bf16_f32 v0, v4, v5
	v_cvt_pk_bf16_f32 v1, v6, v7
	v_cvt_pk_bf16_f32 v2, v2, v3
	v_cvt_pk_bf16_f32 v3, v8, v9
	s_mov_b64 s[20:21], -1
	s_andn2_b64 vcc, exec, s[2:3]
	global_store_dwordx4 v[12:13], v[0:3], off offset:256
	s_cbranch_vccnz .LBB0_1464
	s_andn2_b64 vcc, exec, s[4:5]
	s_cbranch_vccnz .LBB0_1463
	s_barrier
	s_branch .LBB0_1463
